# attention: V^T LDS layout permuted within 16-key groups + 144-byte rows so PV operands are single aligned ds_read_b128 (was ds_read2_b64)
# speedup vs baseline: 1.0053x; 1.0053x over previous
; #define LAS __attribute__((address_space(3)))
;     const int lane = tid & 63, r = lane & 31, hh = lane >> 5;
;     const int wave = __builtin_amdgcn_readfirstlane(tid >> 6), mi = wave & 1, g = wave >> 1;
;     const int w = bid, bh = w & 15, g16 = w >> 4, b = bh >> 3, h = bh & 7;
;     LAS float* lut = (LAS float*)(lds + AT_LUT); LAS float* ex = (LAS float*)lds;
;     const float NEG = -1e30f;
;     __syncthreads();
;     if (tid < 128) lut[tid] = lutg[h * 128 + tid] - rel_tab[31 * 8 + h] * LOG2E;
;     const bf16* kg = Kd + ((size_t)(b * SEQ)) * 1024 + h * 128 + (size_t)(tid >> 4) * 1024 + (tid & 15) * 8;
;     const bf16* vg = VTd + ((size_t)(bh * 128 + (tid >> 3))) * SEQ + (tid & 7) * 8;
;     const int kso = ((tid >> 4) * AT_KSTR + (tid & 15) * 8) * 2, vso = AT_VOFF + ((tid >> 3) * AT_VSTR + (tid & 7) * 8) * 2;
;     for (int ui = 0; ui < 4; ++ui) {
;         const int qb = ui == 0 ? g16 : (ui == 1 ? 31 - g16 : (ui == 2 ? 32 + g16 : 63 - g16));
;         const int qw = qb * 128 + 32 * g, NT = 2 * qb + 2, qabs = qw + r;
;         const bf16* qp = Qd + ((size_t)(b * SEQ + qabs)) * 1024 + h * 128 + 64 * mi + 8 * hh;
.LBB0_292:
	s_cmp_le_i32 s58, s4
	s_cselect_b64 s[4:5], -1, 0
	s_and_b64 s[22:23], s[4:5], s[6:7]
	s_andn2_b64 vcc, exec, s[22:23]
	s_cbranch_vccnz .LBB0_471
	s_mov_b64 s[4:5], s[56:57]
	s_load_dwordx4 s[40:43], s[4:5], 0x38
	s_load_dwordx2 s[6:7], s[4:5], 0x68
	s_ashr_i32 s24, s16, 1
	s_ashr_i32 s25, s24, 31
	s_waitcnt vmcnt(0)
	v_mov_b32_e32 v0, v228
	v_readlane_b32 s4, v254, 0
	s_waitcnt lgkmcnt(0)
	s_add_u32 s26, s6, 0xa0000
	s_addc_u32 s27, s7, 0
	s_lshl_b64 s[18:19], s[24:25], 2
	s_add_u32 s18, s26, s18
	s_addc_u32 s19, s27, s19
	v_mov_b32_e32 v1, 0x1000
	global_load_dword v195, v1, s[18:19]
	global_load_dword v215, v1, s[18:19] offset:8
	s_and_b32 s5, s4, 7
	s_movk_i32 s18, 0x80
	v_readfirstlane_b32 s19, v0
	v_cmp_gt_i32_e32 vcc, s18, v0
	s_lshl_b32 s18, s5, 7
	s_barrier
	s_and_saveexec_b64 s[28:29], vcc
	s_cbranch_execz .LBB0_295
	v_add_u32_e32 v2, s18, v0
	v_ashrrev_i32_e32 v3, 31, v2
	s_lshl_b32 s25, s5, 2
	v_lshl_add_u64 v[2:3], v[2:3], 2, s[26:27]
	v_mov_b32_e32 v1, s25
	global_load_dword v1, v1, s[42:43] offset:992
	s_nop 0
	global_load_dword v2, v[2:3], off
	v_lshl_add_u32 v3, v0, 2, 0
	s_waitcnt vmcnt(0)
	v_fmac_f32_e32 v2, 0xbfb8aa3b, v1
	v_add_u32_e32 v1, 0x11800, v3
	ds_write_b32 v1, v2
.LBB0_295:
	s_or_b64 exec, exec, s[28:29]
	s_lshl_b32 s24, s24, 7
	s_ashr_i32 s25, s24, 31
	s_lshl_b64 s[24:25], s[24:25], 2
	s_add_u32 s34, s40, s24
	s_addc_u32 s35, s41, s25
	s_ashr_i32 s26, s19, 6
	s_ashr_i32 s40, s19, 7
	s_lshl_b32 s19, s4, 10
	s_and_b32 s37, s19, 0x2000
	s_and_b32 s30, s26, 1
	s_and_b32 s24, s4, 15
	s_ashr_i32 s36, s4, 4
	s_lshl_b32 s19, s37, 11
	s_add_u32 s19, s6, s19
	v_ashrrev_i32_e32 v2, 4, v0
	s_addc_u32 s25, s7, 0
	s_lshl_b32 s27, s18, 1
	v_ashrrev_i32_e32 v3, 31, v2
	s_add_u32 s18, s19, s27
	v_lshlrev_b64 v[4:5], 11, v[2:3]
	v_lshlrev_b32_e32 v3, 3, v0
	s_addc_u32 s19, s25, 0
	v_and_b32_e32 v8, 0x78, v3
	v_lshl_add_u64 v[6:7], s[18:19], 0, v[4:5]
	v_lshlrev_b32_e32 v10, 1, v8
	v_mov_b32_e32 v11, v32
	v_ashrrev_i32_e32 v9, 3, v0
	v_lshl_add_u64 v[6:7], v[6:7], 0, v[10:11]
	v_lshl_add_u32 v10, s24, 7, v9
	v_ashrrev_i32_e32 v11, 31, v10
	v_lshlrev_b64 v[10:11], 14, v[10:11]
	v_and_b32_e32 v12, 56, v3
	s_mov_b64 s[18:19], 0x4300000
	v_lshl_add_u64 v[10:11], s[6:7], 0, v[10:11]
	v_lshlrev_b32_e32 v14, 1, v12
	v_mov_b32_e32 v15, v32
	v_lshl_add_u64 v[176:177], v[6:7], 0, s[18:19]
	v_lshl_add_u64 v[10:11], v[10:11], 0, v[14:15]
	s_mov_b64 s[18:19], 0x6300000
	s_movk_i32 s31, 0x88
	v_lshl_add_u64 v[178:179], v[10:11], 0, s[18:19]
	v_mad_u64_u32 v[2:3], s[18:19], v2, s31, v[8:9]
	s_movk_i32 s18, 0x48
	s_nop 0
	v_mad_u64_u32 v[8:9], s[18:19], v9, s18, v[12:13]
	s_lshl_b32 s42, s40, 5
	s_lshl_b32 s24, s30, 7
	s_add_u32 s18, s6, s27
	s_addc_u32 s19, s7, 0
	v_bfe_u32 v1, v0, 5, 1
	s_add_u32 s24, s18, s24
	s_addc_u32 s25, s19, 0
	v_lshlrev_b32_e32 v14, 4, v1
	v_lshl_add_u64 v[16:17], s[24:25], 0, v[14:15]
	s_mov_b64 s[24:25], 0x2300000
	s_cmp_gt_i32 s26, 3
	s_mov_b64 s[28:29], 0x4310000
	v_lshl_add_u64 v[180:181], v[16:17], 0, s[24:25]
	s_cselect_b64 s[24:25], -1, 0
	s_cmp_lt_i32 s26, 4
	v_lshl_add_u64 v[182:183], v[6:7], 0, s[28:29]
	s_mov_b64 s[28:29], 0x6400000
	s_cselect_b64 s[26:27], -1, 0
	v_lshl_add_u64 v[184:185], v[10:11], 0, s[28:29]
	s_mov_b64 s[28:29], 0x4320000
	s_sub_i32 s43, 31, s36
	s_add_i32 s44, s36, 32
	s_sub_i32 s45, 63, s36
	v_and_b32_e32 v218, 31, v0
	v_lshlrev_b32_e32 v12, 3, v1
	v_lshl_add_u64 v[186:187], v[6:7], 0, s[28:29]
	s_mov_b64 s[28:29], 0x4330000
	s_cmp_eq_u32 s30, 0
	v_lshl_add_u32 v219, v2, 1, 0
	v_lshl_add_u64 v[188:189], v[6:7], 0, s[28:29]
	v_mad_u32_u24 v2, v218, s31, v12
	s_cselect_b64 s[28:29], -1, 0
	s_cmp_eq_u32 s30, 1
	v_lshl_add_u32 v3, s30, 6, v2
	s_cselect_b64 s[30:31], -1, 0
	s_lshl_b32 s40, s40, 14
	v_mov_b32_e32 v13, v32
	v_lshl_add_u32 v221, v3, 1, 0
	v_mul_u32_u24_e32 v223, 0x90, v218
	v_lshl_add_u32 v223, v1, 4, v223
	s_add_i32 s40, s40, 0
	v_lshlrev_b32_e32 v2, 9, v1
	v_lshlrev_b32_e32 v3, 2, v218
	v_add3_u32 v224, s40, v2, v3
	v_lshl_add_u64 v[2:3], s[18:19], 0, v[12:13]
	s_mov_b64 s[18:19], 0xa300000
	v_lshl_add_u64 v[190:191], v[2:3], 0, s[18:19]
	v_not_b32_e32 v2, 16
	v_mad_i32_i24 v242, v1, -4, v2
	v_not_b32_e32 v2, 17
	v_mad_i32_i24 v243, v1, -4, v2
	v_not_b32_e32 v2, 18
	v_mad_i32_i24 v244, v1, -4, v2
	v_not_b32_e32 v2, 23
	v_mad_i32_i24 v245, v1, -4, v2
	v_not_b32_e32 v2, 24
	v_mad_i32_i24 v246, v1, -4, v2
	v_not_b32_e32 v2, 25
	s_lshl_b32 s4, s4, 21
	v_mad_i32_i24 v247, v1, -4, v2
	v_not_b32_e32 v2, 26
	s_and_b32 s94, s4, 0x1000000
	v_and_b32_e32 v0, 15, v0
	s_mov_b64 s[18:19], 0x4340000
	v_mad_i32_i24 v248, v1, -4, v2
	v_lshl_add_u64 v[2:3], s[94:95], 0, v[4:5]
	s_lshl_b32 s4, s5, 8
	v_lshlrev_b32_e32 v0, 4, v0
	v_lshl_add_u64 v[204:205], v[6:7], 0, s[18:19]
	s_mov_b64 s[18:19], 0x4350000
	v_or3_b32 v2, v2, s4, v0
	v_mul_i32_i24_e32 v222, -4, v1
	v_lshl_add_u64 v[206:207], v[6:7], 0, s[18:19]
	s_mov_b64 s[18:19], 0x6400080
	v_mad_i32_i24 v225, v1, -4, -1
	v_mad_i32_i24 v226, v1, -4, -2
	v_mad_i32_i24 v227, v1, -4, -3
	v_mad_i32_i24 v237, v1, -4, -8
	v_mad_i32_i24 v238, v1, -4, -9
	v_mad_i32_i24 v239, v1, -4, -10
	v_mad_i32_i24 v240, v1, -4, -11
	v_mad_i32_i24 v241, v1, -4, -16
	v_mad_i32_i24 v249, v1, -4, v218
	v_lshl_add_u64 v[0:1], s[6:7], 0, v[2:3]
	s_mov_b64 s[4:5], 0x4360000
	v_lshl_add_u32 v220, v8, 1, 0
	v_and_b32_e32 v252, 1, v228
	v_lshlrev_b32_e32 v252, 3, v252
	v_sub_u32_e32 v220, v220, v252
	s_mov_b32 s46, 0
	v_lshl_add_u64 v[192:193], s[34:35], 0, v[14:15]
	v_lshl_add_u64 v[208:209], v[10:11], 0, s[18:19]
	v_lshl_add_u64 v[210:211], v[0:1], 0, s[4:5]
	s_branch .LBB0_297

; #define AT_LOADK(t) do { kr0 = *(const v4u*)(kg + (size_t)(t) * 64 * 1024); kr1 = *(const v4u*)(kg + (size_t)(t) * 64 * 1024 + 32 * 1024); } while (0)
; #define AT_LOADV(t) do { vr0 = *(const v4u*)(vg + (t) * 64); vr1 = *(const v4u*)(vg + (size_t)64 * SEQ + (t) * 64); } while (0)
; #define AT_STOREK(bf) do { *(LAS v4u*)(lds + (bf) * AT_KBUF + kso) = kr0; *(LAS v4u*)(lds + (bf) * AT_KBUF + kso + 32 * AT_KSTR * 2) = kr1; } while (0)
; #define AT_STOREV(bf) do { *(LAS v2u*)(lds + (bf) * AT_VBUF + vso) = (v2u){vr0.x, vr0.y}; *(LAS v2u*)(lds + (bf) * AT_VBUF + vso + 8) = (v2u){vr0.z, vr0.w}; \
;         *(LAS v2u*)(lds + (bf) * AT_VBUF + vso + 64 * AT_VSTR * 2) = (v2u){vr1.x, vr1.y}; *(LAS v2u*)(lds + (bf) * AT_VBUF + vso + 64 * AT_VSTR * 2 + 8) = (v2u){vr1.z, vr1.w}; } while (0)
;     ...
;         __syncthreads();
;         AT_LOADK(0); AT_LOADV(0); AT_STOREK(0); AT_STOREV(0); AT_LOADK(1); AT_STOREK(1);
.LBB0_302:
	s_lshl_b32 s19, s4, 7
	s_add_i32 s18, s19, s42
	v_or_b32_e32 v49, s18, v218
	v_add_u32_e32 v212, s37, v49
	v_ashrrev_i32_e32 v213, 31, v212
	v_lshlrev_b64 v[0:1], 11, v[212:213]
	v_lshl_add_u64 v[0:1], v[180:181], 0, v[0:1]
	global_load_dwordx4 v[144:147], v[0:1], off
	global_load_dwordx4 v[148:151], v[0:1], off offset:32
	global_load_dwordx4 v[152:155], v[0:1], off offset:64
	global_load_dwordx4 v[156:159], v[0:1], off offset:96
	s_waitcnt lgkmcnt(0)
	s_barrier
	global_load_dwordx4 v[0:3], v[176:177], off
	global_load_dwordx4 v[4:7], v[182:183], off
	global_load_dwordx4 v[8:11], v[178:179], off
	global_load_dwordx4 v[12:15], v[184:185], off
	s_andn2_b64 vcc, exec, s[24:25]
	s_waitcnt vmcnt(3)
	ds_write_b128 v219, v[0:3]
	s_waitcnt vmcnt(2)
	ds_write_b128 v219, v[4:7] offset:8704
	v_add_u32_e32 v0, 0x8800, v220
	s_waitcnt vmcnt(1)
	ds_write2_b64 v0, v[8:9], v[10:11] offset1:2
	v_add_u32_e32 v0, 0xac00, v220
	s_waitcnt vmcnt(0)
	ds_write2_b64 v0, v[12:13], v[14:15] offset1:2
	global_load_dwordx4 v[160:163], v[186:187], off
	global_load_dwordx4 v[164:167], v[188:189], off
	s_waitcnt vmcnt(1)
	ds_write_b128 v219, v[160:163] offset:17408
	s_waitcnt vmcnt(0)
	ds_write_b128 v219, v[164:167] offset:26112
	s_waitcnt lgkmcnt(0)
	s_barrier
	s_cbranch_vccnz .LBB0_304
	s_barrier

.LBB0_319:
	s_andn2_b64 vcc, exec, s[6:7]
	s_cbranch_vccnz .LBB0_387
	s_cmpk_gt_i32 s18, 0xaf
	s_cbranch_scc1 .LBB0_386
	v_add_u32_e32 v33, v49, v222
	v_cmp_lt_i32_e32 vcc, -1, v33
	v_mov_b32_e32 v50, 0xf149f2ca
	v_mov_b32_e32 v34, 0xf149f2ca
	s_and_saveexec_b64 s[6:7], vcc
	s_cbranch_execz .LBB0_323
	v_min_u32_e32 v34, 0x7f, v33
	v_lshl_add_u32 v34, v34, 2, 0
	v_add_u32_e32 v34, 0x11800, v34
	ds_read_b32 v34, v34
	s_waitcnt lgkmcnt(0)
	v_add_f32_e32 v34, v16, v34
.LBB0_323:
	s_or_b64 exec, exec, s[6:7]
	v_cmp_lt_i32_e32 vcc, 31, v33
	s_and_saveexec_b64 s[6:7], vcc
	s_cbranch_execz .LBB0_325
	v_min_u32_e32 v16, 0x9f, v33
	s_add_i32 s5, 0, 0x11800
	v_lshl_add_u32 v16, v16, 2, s5
	v_add_u32_e32 v16, 0xffffff80, v16
	ds_read_b32 v16, v16
	s_waitcnt lgkmcnt(0)
	v_add_f32_e32 v50, v0, v16
.LBB0_325:
	s_or_b64 exec, exec, s[6:7]
	v_add_u32_e32 v0, v49, v225
	v_cmp_lt_i32_e32 vcc, -1, v0
	v_mov_b32_e32 v51, 0xf149f2ca
	v_mov_b32_e32 v35, 0xf149f2ca
	s_and_saveexec_b64 s[6:7], vcc
	s_cbranch_execz .LBB0_327
	v_min_u32_e32 v16, 0x7f, v0
	v_lshl_add_u32 v16, v16, 2, 0
	v_add_u32_e32 v16, 0x11800, v16
	ds_read_b32 v16, v16
	s_waitcnt lgkmcnt(0)
	v_add_f32_e32 v35, v17, v16
.LBB0_327:
	s_or_b64 exec, exec, s[6:7]
	v_cmp_lt_i32_e32 vcc, 31, v0
	s_and_saveexec_b64 s[6:7], vcc
	s_cbranch_execz .LBB0_329
	v_min_u32_e32 v0, 0x9f, v0
	s_add_i32 s5, 0, 0x11800
	v_lshl_add_u32 v0, v0, 2, s5
	v_add_u32_e32 v0, 0xffffff80, v0
	ds_read_b32 v0, v0
	s_waitcnt lgkmcnt(0)
	v_add_f32_e32 v51, v1, v0
.LBB0_329:
	s_or_b64 exec, exec, s[6:7]
	v_add_u32_e32 v0, v49, v226
	v_cmp_lt_i32_e32 vcc, -1, v0
	v_mov_b32_e32 v52, 0xf149f2ca
	v_mov_b32_e32 v36, 0xf149f2ca
	s_and_saveexec_b64 s[6:7], vcc
	s_cbranch_execz .LBB0_331
	v_min_u32_e32 v1, 0x7f, v0
	v_lshl_add_u32 v1, v1, 2, 0
	v_add_u32_e32 v1, 0x11800, v1
	ds_read_b32 v1, v1
	s_waitcnt lgkmcnt(0)
	v_add_f32_e32 v36, v18, v1
.LBB0_331:
	s_or_b64 exec, exec, s[6:7]
	v_cmp_lt_i32_e32 vcc, 31, v0
	s_and_saveexec_b64 s[6:7], vcc
	s_cbranch_execz .LBB0_333
	v_min_u32_e32 v0, 0x9f, v0
	s_add_i32 s5, 0, 0x11800
	v_lshl_add_u32 v0, v0, 2, s5
	v_add_u32_e32 v0, 0xffffff80, v0
	ds_read_b32 v0, v0
	s_waitcnt lgkmcnt(0)
	v_add_f32_e32 v52, v2, v0
.LBB0_333:
	s_or_b64 exec, exec, s[6:7]
	v_add_u32_e32 v0, v49, v227
	v_cmp_lt_i32_e32 vcc, -1, v0
	v_mov_b32_e32 v53, 0xf149f2ca
	v_mov_b32_e32 v37, 0xf149f2ca
	s_and_saveexec_b64 s[6:7], vcc
	s_cbranch_execz .LBB0_335
	v_min_u32_e32 v1, 0x7f, v0
	v_lshl_add_u32 v1, v1, 2, 0
	v_add_u32_e32 v1, 0x11800, v1
	ds_read_b32 v1, v1
	s_waitcnt lgkmcnt(0)
	v_add_f32_e32 v37, v19, v1
.LBB0_335:
	s_or_b64 exec, exec, s[6:7]
	v_cmp_lt_i32_e32 vcc, 31, v0
	s_and_saveexec_b64 s[6:7], vcc
	s_cbranch_execz .LBB0_337
	v_min_u32_e32 v0, 0x9f, v0
	s_add_i32 s5, 0, 0x11800
	v_lshl_add_u32 v0, v0, 2, s5
	v_add_u32_e32 v0, 0xffffff80, v0
	ds_read_b32 v0, v0
	s_waitcnt lgkmcnt(0)
	v_add_f32_e32 v53, v3, v0
.LBB0_337:
	s_or_b64 exec, exec, s[6:7]
	v_add_u32_e32 v0, v49, v237
	v_cmp_lt_i32_e32 vcc, -1, v0
	v_mov_b32_e32 v54, 0xf149f2ca
	v_mov_b32_e32 v38, 0xf149f2ca
	s_and_saveexec_b64 s[6:7], vcc
	s_cbranch_execz .LBB0_339
	v_min_u32_e32 v1, 0x7f, v0
	v_lshl_add_u32 v1, v1, 2, 0
	v_add_u32_e32 v1, 0x11800, v1
	ds_read_b32 v1, v1
	s_waitcnt lgkmcnt(0)
	v_add_f32_e32 v38, v20, v1
.LBB0_339:
	s_or_b64 exec, exec, s[6:7]
	v_cmp_lt_i32_e32 vcc, 31, v0
	s_and_saveexec_b64 s[6:7], vcc
	s_cbranch_execz .LBB0_341
	v_min_u32_e32 v0, 0x9f, v0
	s_add_i32 s5, 0, 0x11800
	v_lshl_add_u32 v0, v0, 2, s5
	v_add_u32_e32 v0, 0xffffff80, v0
	ds_read_b32 v0, v0
	s_waitcnt lgkmcnt(0)
	v_add_f32_e32 v54, v4, v0
.LBB0_341:
	s_or_b64 exec, exec, s[6:7]
	v_add_u32_e32 v0, v49, v238
	v_cmp_lt_i32_e32 vcc, -1, v0
	v_mov_b32_e32 v55, 0xf149f2ca
	v_mov_b32_e32 v39, 0xf149f2ca
	s_and_saveexec_b64 s[6:7], vcc
	s_cbranch_execz .LBB0_343
	v_min_u32_e32 v1, 0x7f, v0
	v_lshl_add_u32 v1, v1, 2, 0
	v_add_u32_e32 v1, 0x11800, v1
	ds_read_b32 v1, v1
	s_waitcnt lgkmcnt(0)
	v_add_f32_e32 v39, v21, v1
.LBB0_343:
	s_or_b64 exec, exec, s[6:7]
	v_cmp_lt_i32_e32 vcc, 31, v0
	s_and_saveexec_b64 s[6:7], vcc
	s_cbranch_execz .LBB0_345
	v_min_u32_e32 v0, 0x9f, v0
	s_add_i32 s5, 0, 0x11800
	v_lshl_add_u32 v0, v0, 2, s5
	v_add_u32_e32 v0, 0xffffff80, v0
	ds_read_b32 v0, v0
	s_waitcnt lgkmcnt(0)
	v_add_f32_e32 v55, v5, v0
.LBB0_345:
	s_or_b64 exec, exec, s[6:7]
	v_add_u32_e32 v0, v49, v239
	v_cmp_lt_i32_e32 vcc, -1, v0
	v_mov_b32_e32 v56, 0xf149f2ca
	v_mov_b32_e32 v40, 0xf149f2ca
	s_and_saveexec_b64 s[6:7], vcc
	s_cbranch_execz .LBB0_347
	v_min_u32_e32 v1, 0x7f, v0
	v_lshl_add_u32 v1, v1, 2, 0
	v_add_u32_e32 v1, 0x11800, v1
	ds_read_b32 v1, v1
	s_waitcnt lgkmcnt(0)
	v_add_f32_e32 v40, v22, v1
.LBB0_347:
	s_or_b64 exec, exec, s[6:7]
	v_cmp_lt_i32_e32 vcc, 31, v0
	s_and_saveexec_b64 s[6:7], vcc
	s_cbranch_execz .LBB0_349
	v_min_u32_e32 v0, 0x9f, v0
	s_add_i32 s5, 0, 0x11800
	v_lshl_add_u32 v0, v0, 2, s5
	v_add_u32_e32 v0, 0xffffff80, v0
	ds_read_b32 v0, v0
	s_waitcnt lgkmcnt(0)
	v_add_f32_e32 v56, v6, v0
.LBB0_349:
	s_or_b64 exec, exec, s[6:7]
	v_add_u32_e32 v0, v49, v240
	v_cmp_lt_i32_e32 vcc, -1, v0
	v_mov_b32_e32 v57, 0xf149f2ca
	v_mov_b32_e32 v41, 0xf149f2ca
	s_and_saveexec_b64 s[6:7], vcc
	s_cbranch_execz .LBB0_351
	v_min_u32_e32 v1, 0x7f, v0
	v_lshl_add_u32 v1, v1, 2, 0
	v_add_u32_e32 v1, 0x11800, v1
	ds_read_b32 v1, v1
	s_waitcnt lgkmcnt(0)
	v_add_f32_e32 v41, v23, v1
.LBB0_351:
	s_or_b64 exec, exec, s[6:7]
	v_cmp_lt_i32_e32 vcc, 31, v0
	s_and_saveexec_b64 s[6:7], vcc
	s_cbranch_execz .LBB0_353
	v_min_u32_e32 v0, 0x9f, v0
	s_add_i32 s5, 0, 0x11800
	v_lshl_add_u32 v0, v0, 2, s5
	v_add_u32_e32 v0, 0xffffff80, v0
	ds_read_b32 v0, v0
	s_waitcnt lgkmcnt(0)
	v_add_f32_e32 v57, v7, v0
.LBB0_353:
	s_or_b64 exec, exec, s[6:7]
	v_add_u32_e32 v0, v49, v241
	v_cmp_lt_i32_e32 vcc, -1, v0
	v_mov_b32_e32 v58, 0xf149f2ca
	v_mov_b32_e32 v42, 0xf149f2ca
	s_and_saveexec_b64 s[6:7], vcc
	s_cbranch_execz .LBB0_355
	v_min_u32_e32 v1, 0x7f, v0
	v_lshl_add_u32 v1, v1, 2, 0
	v_add_u32_e32 v1, 0x11800, v1
	ds_read_b32 v1, v1
	s_waitcnt lgkmcnt(0)
	v_add_f32_e32 v42, v24, v1
.LBB0_355:
	s_or_b64 exec, exec, s[6:7]
	v_cmp_lt_i32_e32 vcc, 31, v0
	s_and_saveexec_b64 s[6:7], vcc
	s_cbranch_execz .LBB0_357
	v_min_u32_e32 v0, 0x9f, v0
	s_add_i32 s5, 0, 0x11800
	v_lshl_add_u32 v0, v0, 2, s5
	v_add_u32_e32 v0, 0xffffff80, v0
	ds_read_b32 v0, v0
	s_waitcnt lgkmcnt(0)
	v_add_f32_e32 v58, v8, v0
.LBB0_357:
	s_or_b64 exec, exec, s[6:7]
	v_add_u32_e32 v0, v49, v242
	v_cmp_lt_i32_e32 vcc, -1, v0
	v_mov_b32_e32 v59, 0xf149f2ca
	v_mov_b32_e32 v43, 0xf149f2ca
	s_and_saveexec_b64 s[6:7], vcc
	s_cbranch_execz .LBB0_359
	v_min_u32_e32 v1, 0x7f, v0
	v_lshl_add_u32 v1, v1, 2, 0
	v_add_u32_e32 v1, 0x11800, v1
	ds_read_b32 v1, v1
	s_waitcnt lgkmcnt(0)
	v_add_f32_e32 v43, v25, v1
.LBB0_359:
	s_or_b64 exec, exec, s[6:7]
	v_cmp_lt_i32_e32 vcc, 31, v0
	s_and_saveexec_b64 s[6:7], vcc
	s_cbranch_execz .LBB0_361
	v_min_u32_e32 v0, 0x9f, v0
	s_add_i32 s5, 0, 0x11800
	v_lshl_add_u32 v0, v0, 2, s5
	v_add_u32_e32 v0, 0xffffff80, v0
	ds_read_b32 v0, v0
	s_waitcnt lgkmcnt(0)
	v_add_f32_e32 v59, v9, v0
.LBB0_361:
	s_or_b64 exec, exec, s[6:7]
	v_add_u32_e32 v0, v49, v243
	v_cmp_lt_i32_e32 vcc, -1, v0
	v_mov_b32_e32 v60, 0xf149f2ca
	v_mov_b32_e32 v44, 0xf149f2ca
	s_and_saveexec_b64 s[6:7], vcc
	s_cbranch_execz .LBB0_363
	v_min_u32_e32 v1, 0x7f, v0
	v_lshl_add_u32 v1, v1, 2, 0
	v_add_u32_e32 v1, 0x11800, v1
	ds_read_b32 v1, v1
	s_waitcnt lgkmcnt(0)
	v_add_f32_e32 v44, v26, v1
.LBB0_363:
	s_or_b64 exec, exec, s[6:7]
	v_cmp_lt_i32_e32 vcc, 31, v0
	s_and_saveexec_b64 s[6:7], vcc
	s_cbranch_execz .LBB0_365
	v_min_u32_e32 v0, 0x9f, v0
	s_add_i32 s5, 0, 0x11800
	v_lshl_add_u32 v0, v0, 2, s5
	v_add_u32_e32 v0, 0xffffff80, v0
	ds_read_b32 v0, v0
	s_waitcnt lgkmcnt(0)
	v_add_f32_e32 v60, v10, v0
.LBB0_365:
	s_or_b64 exec, exec, s[6:7]
	v_add_u32_e32 v0, v49, v244
	v_cmp_lt_i32_e32 vcc, -1, v0
	v_mov_b32_e32 v61, 0xf149f2ca
	v_mov_b32_e32 v45, 0xf149f2ca
	s_and_saveexec_b64 s[6:7], vcc
	s_cbranch_execz .LBB0_367
	v_min_u32_e32 v1, 0x7f, v0
	v_lshl_add_u32 v1, v1, 2, 0
	v_add_u32_e32 v1, 0x11800, v1
	ds_read_b32 v1, v1
	s_waitcnt lgkmcnt(0)
	v_add_f32_e32 v45, v27, v1
.LBB0_367:
	s_or_b64 exec, exec, s[6:7]
	v_cmp_lt_i32_e32 vcc, 31, v0
	s_and_saveexec_b64 s[6:7], vcc
	s_cbranch_execz .LBB0_369
	v_min_u32_e32 v0, 0x9f, v0
	s_add_i32 s5, 0, 0x11800
	v_lshl_add_u32 v0, v0, 2, s5
	v_add_u32_e32 v0, 0xffffff80, v0
	ds_read_b32 v0, v0
	s_waitcnt lgkmcnt(0)
	v_add_f32_e32 v61, v11, v0
.LBB0_369:
	s_or_b64 exec, exec, s[6:7]
	v_add_u32_e32 v0, v49, v245
	v_cmp_lt_i32_e32 vcc, -1, v0
	v_mov_b32_e32 v62, 0xf149f2ca
	v_mov_b32_e32 v46, 0xf149f2ca
	s_and_saveexec_b64 s[6:7], vcc
	s_cbranch_execz .LBB0_371
	v_min_u32_e32 v1, 0x7f, v0
	v_lshl_add_u32 v1, v1, 2, 0
	v_add_u32_e32 v1, 0x11800, v1
	ds_read_b32 v1, v1
	s_waitcnt lgkmcnt(0)
	v_add_f32_e32 v46, v28, v1
.LBB0_371:
	s_or_b64 exec, exec, s[6:7]
	v_cmp_lt_i32_e32 vcc, 31, v0
	s_and_saveexec_b64 s[6:7], vcc
	s_cbranch_execz .LBB0_373
	v_min_u32_e32 v0, 0x9f, v0
	s_add_i32 s5, 0, 0x11800
	v_lshl_add_u32 v0, v0, 2, s5
	v_add_u32_e32 v0, 0xffffff80, v0
	ds_read_b32 v0, v0
	s_waitcnt lgkmcnt(0)
	v_add_f32_e32 v62, v12, v0
.LBB0_373:
	s_or_b64 exec, exec, s[6:7]
	v_add_u32_e32 v0, v49, v246
	v_cmp_lt_i32_e32 vcc, -1, v0
	v_mov_b32_e32 v63, 0xf149f2ca
	v_mov_b32_e32 v47, 0xf149f2ca
	s_and_saveexec_b64 s[6:7], vcc
	s_cbranch_execz .LBB0_375
	v_min_u32_e32 v1, 0x7f, v0
	v_lshl_add_u32 v1, v1, 2, 0
	v_add_u32_e32 v1, 0x11800, v1
	ds_read_b32 v1, v1
	s_waitcnt lgkmcnt(0)
	v_add_f32_e32 v47, v29, v1
.LBB0_375:
	s_or_b64 exec, exec, s[6:7]
	v_cmp_lt_i32_e32 vcc, 31, v0
	s_and_saveexec_b64 s[6:7], vcc
	s_cbranch_execz .LBB0_377
	v_min_u32_e32 v0, 0x9f, v0
	s_add_i32 s5, 0, 0x11800
	v_lshl_add_u32 v0, v0, 2, s5
	v_add_u32_e32 v0, 0xffffff80, v0
	ds_read_b32 v0, v0
	s_waitcnt lgkmcnt(0)
	v_add_f32_e32 v63, v13, v0
.LBB0_377:
	s_or_b64 exec, exec, s[6:7]
	v_add_u32_e32 v0, v49, v247
	v_cmp_lt_i32_e32 vcc, -1, v0
	v_mov_b32_e32 v64, 0xf149f2ca
	v_mov_b32_e32 v48, 0xf149f2ca
	s_and_saveexec_b64 s[6:7], vcc
	s_cbranch_execz .LBB0_379
	v_min_u32_e32 v1, 0x7f, v0
	v_lshl_add_u32 v1, v1, 2, 0
	v_add_u32_e32 v1, 0x11800, v1
	ds_read_b32 v1, v1
	s_waitcnt lgkmcnt(0)
	v_add_f32_e32 v48, v30, v1
.LBB0_379:
	s_or_b64 exec, exec, s[6:7]
	v_cmp_lt_i32_e32 vcc, 31, v0
	s_and_saveexec_b64 s[6:7], vcc
	s_cbranch_execz .LBB0_381
	v_min_u32_e32 v0, 0x9f, v0
	s_add_i32 s5, 0, 0x11800
	v_lshl_add_u32 v0, v0, 2, s5
	v_add_u32_e32 v0, 0xffffff80, v0
	ds_read_b32 v0, v0
	s_waitcnt lgkmcnt(0)
	v_add_f32_e32 v64, v14, v0
.LBB0_381:
	s_or_b64 exec, exec, s[6:7]
	v_add_u32_e32 v0, v49, v248
	v_cmp_lt_i32_e32 vcc, -1, v0
	v_mov_b32_e32 v65, 0xf149f2ca
	v_mov_b32_e32 v49, 0xf149f2ca
	s_and_saveexec_b64 s[6:7], vcc
	s_cbranch_execz .LBB0_383
	v_min_u32_e32 v1, 0x7f, v0
	v_lshl_add_u32 v1, v1, 2, 0
	v_add_u32_e32 v1, 0x11800, v1
	ds_read_b32 v1, v1
	s_waitcnt lgkmcnt(0)
	v_add_f32_e32 v49, v31, v1
.LBB0_383:
	s_or_b64 exec, exec, s[6:7]
	v_cmp_lt_i32_e32 vcc, 31, v0
	s_and_saveexec_b64 s[6:7], vcc
	s_cbranch_execz .LBB0_385
	v_min_u32_e32 v0, 0x9f, v0
	s_add_i32 s5, 0, 0x11800
	v_lshl_add_u32 v0, v0, 2, s5
	v_add_u32_e32 v0, 0xffffff80, v0
	ds_read_b32 v0, v0
	s_waitcnt lgkmcnt(0)
	v_add_f32_e32 v65, v15, v0

.LBB0_386:
	v_max3_f32 v33, v16, v17, v0
	v_max3_f32 v34, v18, v19, v1
	s_cmp_eq_u64 exec, 0
	v_max3_f32 v33, v33, v2, v3
	v_max3_f32 v34, v34, v22, v23
	s_cselect_b64 s[40:41], -1, 0
	v_max3_f32 v33, v33, v20, v21
	v_max3_f32 v34, v34, v6, v7
	v_add_u32_e32 v46, 0x9800, v223
	v_max3_f32 v33, v33, v4, v5
	v_max3_f32 v34, v34, v26, v27
	s_nop 0
	v_max3_f32 v33, v33, v24, v25
	v_max3_f32 v34, v34, v10, v11
	s_nop 0
	v_max3_f32 v33, v33, v8, v9
	v_max3_f32 v34, v34, v30, v31
	s_nop 0
	v_max3_f32 v33, v33, v28, v29
	v_max3_f32 v34, v34, v14, v15
	s_nop 0
	v_max3_f32 v33, v33, v12, v13
	v_max_f32_e32 v34, v34, v34
	v_max_f32_e32 v33, v33, v33
	v_max_f32_e32 v33, v33, v34
	v_mov_b32_e32 v34, v33
	s_nop 1
	v_permlane32_swap_b32_e32 v33, v34
	v_max_f32_e32 v34, v34, v34
	v_max_f32_e32 v33, v33, v33
	v_max_f32_e32 v33, v33, v34
	v_add_f32_e32 v33, 0, v33
	v_cndmask_b32_e64 v214, v33, 0, s[40:41]
	v_sub_f32_e32 v16, v16, v214
	v_sub_f32_e32 v17, v17, v214
	v_sub_f32_e32 v0, v0, v214
	v_sub_f32_e32 v1, v1, v214
	v_exp_f32_e32 v16, v16
	v_exp_f32_e32 v17, v17
	v_exp_f32_e32 v38, v0
	v_exp_f32_e32 v39, v1
	v_sub_f32_e32 v18, v18, v214
	v_sub_f32_e32 v19, v19, v214
	v_sub_f32_e32 v2, v2, v214
	v_sub_f32_e32 v3, v3, v214
	v_exp_f32_e32 v18, v18
	v_exp_f32_e32 v19, v19
	v_exp_f32_e32 v40, v2
	v_exp_f32_e32 v41, v3
	v_sub_f32_e32 v2, v20, v214
	v_sub_f32_e32 v3, v21, v214
	v_add_f32_e32 v0, 0, v16
	v_add_f32_e32 v1, 0, v17
	v_sub_f32_e32 v4, v4, v214
	v_sub_f32_e32 v5, v5, v214
	v_exp_f32_e32 v2, v2
	v_exp_f32_e32 v3, v3
	v_add_f32_e32 v0, v38, v0
	v_add_f32_e32 v1, v39, v1
	v_exp_f32_e32 v4, v4
	v_exp_f32_e32 v5, v5
	v_sub_f32_e32 v20, v22, v214
	v_sub_f32_e32 v21, v23, v214
	v_add_f32_e32 v0, v18, v0
	v_add_f32_e32 v1, v19, v1
	v_sub_f32_e32 v6, v6, v214
	v_sub_f32_e32 v7, v7, v214
	v_exp_f32_e32 v20, v20
	v_exp_f32_e32 v21, v21
	v_add_f32_e32 v0, v40, v0
	v_add_f32_e32 v1, v41, v1
	v_exp_f32_e32 v6, v6
	v_exp_f32_e32 v7, v7
	v_sub_f32_e32 v22, v24, v214
	v_sub_f32_e32 v23, v25, v214
	v_add_f32_e32 v0, v2, v0
	v_add_f32_e32 v1, v3, v1
	v_sub_f32_e32 v8, v8, v214
	v_sub_f32_e32 v9, v9, v214
	v_exp_f32_e32 v22, v22
	v_exp_f32_e32 v23, v23
	v_add_f32_e32 v0, v4, v0
	v_add_f32_e32 v1, v5, v1
	v_exp_f32_e32 v8, v8
	v_exp_f32_e32 v9, v9
	v_sub_f32_e32 v24, v26, v214
	v_sub_f32_e32 v25, v27, v214
	v_add_f32_e32 v0, v20, v0
	v_add_f32_e32 v1, v21, v1
	v_sub_f32_e32 v10, v10, v214
	v_sub_f32_e32 v11, v11, v214
	v_exp_f32_e32 v24, v24
	v_exp_f32_e32 v25, v25
	v_add_f32_e32 v0, v6, v0
	v_add_f32_e32 v1, v7, v1
	v_exp_f32_e32 v10, v10
	v_exp_f32_e32 v11, v11
	v_sub_f32_e32 v26, v28, v214
	v_sub_f32_e32 v27, v29, v214
	v_add_f32_e32 v0, v22, v0
	v_add_f32_e32 v1, v23, v1
	v_sub_f32_e32 v12, v12, v214
	v_sub_f32_e32 v13, v13, v214
	v_exp_f32_e32 v26, v26
	v_exp_f32_e32 v27, v27
	v_add_f32_e32 v0, v8, v0
	v_add_f32_e32 v1, v9, v1
	v_exp_f32_e32 v12, v12
	v_exp_f32_e32 v13, v13
	v_add_f32_e32 v0, v24, v0
	v_add_f32_e32 v1, v25, v1
	v_sub_f32_e32 v14, v14, v214
	v_sub_f32_e32 v15, v15, v214
	v_add_f32_e32 v0, v10, v0
	v_add_f32_e32 v1, v11, v1
	v_exp_f32_e32 v14, v14
	v_add_f32_e32 v0, v26, v0
	v_add_f32_e32 v1, v27, v1
	v_exp_f32_e32 v15, v15
	v_add_f32_e32 v28, v12, v0
	v_add_f32_e32 v29, v13, v1
	v_sub_f32_e32 v0, v30, v214
	v_sub_f32_e32 v1, v31, v214
	v_add_u32_e32 v33, 0x8800, v223
	v_exp_f32_e32 v30, v0
	v_exp_f32_e32 v31, v1
	v_cvt_pk_bf16_f32 v0, v16, v17
	v_cvt_pk_bf16_f32 v1, v18, v19
	v_cvt_pk_bf16_f32 v2, v2, v3
	v_cvt_pk_bf16_f32 v3, v20, v21
	v_cvt_pk_bf16_f32 v34, v22, v23
	v_cvt_pk_bf16_f32 v35, v24, v25
	v_cvt_pk_bf16_f32 v36, v26, v27
	v_cvt_pk_bf16_f32 v37, v30, v31
	v_cvt_pk_bf16_f32 v38, v38, v39
	v_cvt_pk_bf16_f32 v39, v40, v41
	v_cvt_pk_bf16_f32 v40, v4, v5
	v_cvt_pk_bf16_f32 v41, v6, v7
	v_cvt_pk_bf16_f32 v42, v8, v9
	v_cvt_pk_bf16_f32 v43, v10, v11
	v_cvt_pk_bf16_f32 v44, v12, v13
	v_cvt_pk_bf16_f32 v45, v14, v15
	s_setprio 0
	s_barrier
	ds_read_b128 v[4:7], v33
	ds_read_b128 v[8:11], v46 offset:512
	v_add_f32_e32 v12, v30, v28
	v_add_f32_e32 v13, v31, v29
	s_nop 0
	v_add_f32_e32 v12, v14, v12
	v_add_f32_e32 v13, v15, v13
	s_nop 0
	v_add_f32_e32 v12, v12, v13
	v_add_f32_e32 v250, 0, v12
	v_add_u32_e32 v47, 0xa800, v223
	ds_read_b128 v[12:15], v47 offset:1024
	v_add_u32_e32 v104, 0xb800, v223
	ds_read_b128 v[80:83], v104 offset:1536
	ds_read_b128 v[84:87], v33 offset:32
	ds_read_b128 v[88:91], v46 offset:544
	s_waitcnt lgkmcnt(5)
	v_mfma_f32_32x32x16_bf16 v[64:79], v[4:7], v[0:3], 0
	s_waitcnt lgkmcnt(4)
	v_mfma_f32_32x32x16_bf16 v[48:63], v[8:11], v[0:3], 0
	ds_read_b128 v[92:95], v47 offset:1056
	ds_read_b128 v[96:99], v104 offset:1568
	s_waitcnt lgkmcnt(5)
	v_mfma_f32_32x32x16_bf16 v[16:31], v[12:15], v[0:3], 0
	s_waitcnt lgkmcnt(4)
	v_mfma_f32_32x32x16_bf16 v[0:15], v[80:83], v[0:3], 0
	ds_read_b128 v[80:83], v33 offset:64
	ds_read_b128 v[100:103], v46 offset:576
	s_waitcnt lgkmcnt(5)
	v_mfma_f32_32x32x16_bf16 v[64:79], v[84:87], v[34:37], v[64:79]
	s_waitcnt lgkmcnt(4)
	v_mfma_f32_32x32x16_bf16 v[48:63], v[88:91], v[34:37], v[48:63]
	ds_read_b128 v[84:87], v47 offset:1088
	ds_read_b128 v[88:91], v104 offset:1600
	s_waitcnt lgkmcnt(5)
	v_mfma_f32_32x32x16_bf16 v[16:31], v[92:95], v[34:37], v[16:31]
	s_waitcnt lgkmcnt(4)
	v_mfma_f32_32x32x16_bf16 v[0:15], v[96:99], v[34:37], v[0:15]
	ds_read_b128 v[34:37], v33 offset:96
	ds_read_b128 v[92:95], v46 offset:608
	s_waitcnt lgkmcnt(5)
	v_mfma_f32_32x32x16_bf16 v[64:79], v[80:83], v[38:41], v[64:79]
	s_waitcnt lgkmcnt(4)
	v_mfma_f32_32x32x16_bf16 v[48:63], v[100:103], v[38:41], v[48:63]
	ds_read_b128 v[80:83], v47 offset:1120
	ds_read_b128 v[96:99], v104 offset:1632
	s_waitcnt lgkmcnt(5)
	v_mfma_f32_32x32x16_bf16 v[16:31], v[84:87], v[38:41], v[16:31]
	s_waitcnt lgkmcnt(4)
	v_mfma_f32_32x32x16_bf16 v[0:15], v[88:91], v[38:41], v[0:15]
	s_waitcnt lgkmcnt(3)
	v_mfma_f32_32x32x16_bf16 v[64:79], v[34:37], v[42:45], v[64:79]
	s_waitcnt lgkmcnt(2)
	v_mfma_f32_32x32x16_bf16 v[48:63], v[92:95], v[42:45], v[48:63]
	s_waitcnt lgkmcnt(1)
	v_mfma_f32_32x32x16_bf16 v[16:31], v[80:83], v[42:45], v[16:31]
	s_waitcnt lgkmcnt(0)
	v_mfma_f32_32x32x16_bf16 v[0:15], v[96:99], v[42:45], v[0:15]
	s_branch .LBB0_388

; #define AT_LOADK(t) do { kr0 = *(const v4u*)(kg + (size_t)(t) * 64 * 1024); kr1 = *(const v4u*)(kg + (size_t)(t) * 64 * 1024 + 32 * 1024); } while (0)
; #define AT_LOADV(t) do { vr0 = *(const v4u*)(vg + (t) * 64); vr1 = *(const v4u*)(vg + (size_t)64 * SEQ + (t) * 64); } while (0)
; #define AT_STOREK(bf) do { *(LAS v4u*)(lds + (bf) * AT_KBUF + kso) = kr0; *(LAS v4u*)(lds + (bf) * AT_KBUF + kso + 32 * AT_KSTR * 2) = kr1; } while (0)
; #define AT_STOREV(bf) do { *(LAS v2u*)(lds + (bf) * AT_VBUF + vso) = (v2u){vr0.x, vr0.y}; *(LAS v2u*)(lds + (bf) * AT_VBUF + vso + 8) = (v2u){vr0.z, vr0.w}; \
;         *(LAS v2u*)(lds + (bf) * AT_VBUF + vso + 64 * AT_VSTR * 2) = (v2u){vr1.x, vr1.y}; *(LAS v2u*)(lds + (bf) * AT_VBUF + vso + 64 * AT_VSTR * 2 + 8) = (v2u){vr1.z, vr1.w}; } while (0)
;     ...
;             if (!(AMODE & 4) && t >= 1) { if (t + 1 < NT) AT_STOREK((t + 1) & 1); if (t < NT) AT_STOREV(t & 1); }
;             __syncthreads();
;             if (!(AMODE & 4)) { if (t + 2 < NT) AT_LOADK(t + 2); if (t + 1 < NT) AT_LOADV(t + 1); }
.LBB0_393:
	s_bitcmp1_b32 s50, 0
	s_cselect_b32 s49, 0x4800, 0
	v_add_u32_e32 v33, s49, v220
	v_add_u32_e32 v34, 0x8800, v33
	v_add_u32_e32 v33, 0xac00, v33
	s_cmp_ge_i32 s50, s4
	s_waitcnt vmcnt(1)
	ds_write2_b64 v34, v[168:169], v[170:171] offset1:2
	s_waitcnt vmcnt(0)
	ds_write2_b64 v33, v[172:173], v[174:175] offset1:2
	s_waitcnt lgkmcnt(0)
	s_barrier
	s_setprio 1
	global_load_dwordx4 v[160:163], v[216:217], off
	s_mov_b64 s[66:67], 0x10000
	s_and_b64 vcc, exec, s[6:7]
	s_cbranch_vccz .LBB0_400

.LBB0_400:
	s_add_i32 s6, s42, s19
	s_cmpk_gt_i32 s6, 0xaf
	s_cbranch_scc1 .LBB0_466
	v_add_u32_e32 v33, s42, v251
	s_mov_b32 s50, 0x11800
	s_mov_b32 s51, 0x11780
	v_mov_b32_e32 v47, 0xf149f2ca
	v_add_u32_e32 v34, 0xffffffc0, v33
	v_min_u32_e32 v36, 0x7f, v34
	v_min_u32_e32 v37, 0x9f, v34
	v_lshl_add_u32 v36, v36, 2, s50
	v_lshl_add_u32 v37, v37, 2, s51
	ds_read_b32 v112, v36
	ds_read_b32 v128, v37
	v_add_u32_e32 v34, 0xffffffbf, v33
	v_min_u32_e32 v38, 0x7f, v34
	v_min_u32_e32 v39, 0x9f, v34
	v_lshl_add_u32 v38, v38, 2, s50
	v_lshl_add_u32 v39, v39, 2, s51
	ds_read_b32 v113, v38
	ds_read_b32 v129, v39
	v_add_u32_e32 v34, 0xffffffbe, v33
	v_min_u32_e32 v40, 0x7f, v34
	v_min_u32_e32 v41, 0x9f, v34
	v_lshl_add_u32 v40, v40, 2, s50
	v_lshl_add_u32 v41, v41, 2, s51
	ds_read_b32 v114, v40
	ds_read_b32 v130, v41
	v_add_u32_e32 v34, 0xffffffbd, v33
	v_min_u32_e32 v42, 0x7f, v34
	v_min_u32_e32 v43, 0x9f, v34
	v_lshl_add_u32 v42, v42, 2, s50
	v_lshl_add_u32 v43, v43, 2, s51
	ds_read_b32 v115, v42
	ds_read_b32 v131, v43
	v_add_u32_e32 v34, 0xffffffb8, v33
	v_min_u32_e32 v36, 0x7f, v34
	v_min_u32_e32 v37, 0x9f, v34
	v_lshl_add_u32 v36, v36, 2, s50
	v_lshl_add_u32 v37, v37, 2, s51
	ds_read_b32 v116, v36
	ds_read_b32 v132, v37
	v_add_u32_e32 v34, 0xffffffb7, v33
	v_min_u32_e32 v38, 0x7f, v34
	v_min_u32_e32 v39, 0x9f, v34
	v_lshl_add_u32 v38, v38, 2, s50
	v_lshl_add_u32 v39, v39, 2, s51
	ds_read_b32 v117, v38
	ds_read_b32 v133, v39
	s_waitcnt lgkmcnt(0)
	v_add_u32_e32 v34, 0xffffffb6, v33
	v_min_u32_e32 v40, 0x7f, v34
	v_min_u32_e32 v41, 0x9f, v34
	v_lshl_add_u32 v40, v40, 2, s50
	v_lshl_add_u32 v41, v41, 2, s51
	ds_read_b32 v118, v40
	ds_read_b32 v134, v41
	v_add_u32_e32 v34, 0xffffffb5, v33
	v_min_u32_e32 v42, 0x7f, v34
	v_min_u32_e32 v43, 0x9f, v34
	v_lshl_add_u32 v42, v42, 2, s50
	v_lshl_add_u32 v43, v43, 2, s51
	ds_read_b32 v119, v42
	ds_read_b32 v135, v43
	v_add_u32_e32 v34, 0xffffffb0, v33
	v_min_u32_e32 v36, 0x7f, v34
	v_min_u32_e32 v37, 0x9f, v34
	v_lshl_add_u32 v36, v36, 2, s50
	v_lshl_add_u32 v37, v37, 2, s51
	ds_read_b32 v120, v36
	ds_read_b32 v136, v37
	v_add_u32_e32 v34, 0xffffffaf, v33
	v_min_u32_e32 v38, 0x7f, v34
	v_min_u32_e32 v39, 0x9f, v34
	v_lshl_add_u32 v38, v38, 2, s50
	v_lshl_add_u32 v39, v39, 2, s51
	ds_read_b32 v121, v38
	ds_read_b32 v137, v39
	v_add_u32_e32 v34, 0xffffffae, v33
	v_min_u32_e32 v40, 0x7f, v34
	v_min_u32_e32 v41, 0x9f, v34
	v_lshl_add_u32 v40, v40, 2, s50
	v_lshl_add_u32 v41, v41, 2, s51
	ds_read_b32 v122, v40
	ds_read_b32 v138, v41
	v_add_u32_e32 v34, 0xffffffad, v33
	v_min_u32_e32 v42, 0x7f, v34
	v_min_u32_e32 v43, 0x9f, v34
	v_lshl_add_u32 v42, v42, 2, s50
	v_lshl_add_u32 v43, v43, 2, s51
	ds_read_b32 v123, v42
	ds_read_b32 v139, v43
	v_add_u32_e32 v34, 0xffffffc0, v33
	v_cmp_lt_i32_e64 s[6:7], -1, v34
	v_cmp_lt_i32_e64 s[60:61], 31, v34
	v_add_f32_e32 v112, v96, v112
	v_add_f32_e32 v128, v80, v128
	v_cndmask_b32_e64 v96, v47, v112, s[6:7]
	v_cndmask_b32_e64 v80, v47, v128, s[60:61]
	v_add_u32_e32 v34, 0xffffffbf, v33
	v_cmp_lt_i32_e64 s[6:7], -1, v34
	v_cmp_lt_i32_e64 s[60:61], 31, v34
	v_add_f32_e32 v113, v97, v113
	v_add_f32_e32 v129, v81, v129
	v_cndmask_b32_e64 v97, v47, v113, s[6:7]
	v_cndmask_b32_e64 v81, v47, v129, s[60:61]
	v_add_u32_e32 v34, 0xffffffbe, v33
	v_cmp_lt_i32_e64 s[6:7], -1, v34
	v_cmp_lt_i32_e64 s[60:61], 31, v34
	v_add_f32_e32 v114, v98, v114
	v_add_f32_e32 v130, v82, v130
	v_cndmask_b32_e64 v98, v47, v114, s[6:7]
	v_cndmask_b32_e64 v82, v47, v130, s[60:61]
	v_add_u32_e32 v34, 0xffffffbd, v33
	v_cmp_lt_i32_e64 s[6:7], -1, v34
	v_cmp_lt_i32_e64 s[60:61], 31, v34
	v_add_f32_e32 v115, v99, v115
	v_add_f32_e32 v131, v83, v131
	v_cndmask_b32_e64 v99, v47, v115, s[6:7]
	v_cndmask_b32_e64 v83, v47, v131, s[60:61]
	v_add_u32_e32 v34, 0xffffffb8, v33
	v_cmp_lt_i32_e64 s[6:7], -1, v34
	v_cmp_lt_i32_e64 s[60:61], 31, v34
	v_add_f32_e32 v116, v100, v116
	v_add_f32_e32 v132, v84, v132
	v_cndmask_b32_e64 v100, v47, v116, s[6:7]
	v_cndmask_b32_e64 v84, v47, v132, s[60:61]
	v_add_u32_e32 v34, 0xffffffb7, v33
	v_cmp_lt_i32_e64 s[6:7], -1, v34
	v_cmp_lt_i32_e64 s[60:61], 31, v34
	v_add_f32_e32 v117, v101, v117
	v_add_f32_e32 v133, v85, v133
	v_cndmask_b32_e64 v101, v47, v117, s[6:7]
	v_cndmask_b32_e64 v85, v47, v133, s[60:61]
	s_waitcnt lgkmcnt(0)
	v_add_u32_e32 v34, 0xffffffa8, v33
	v_min_u32_e32 v36, 0x7f, v34
	v_min_u32_e32 v37, 0x9f, v34
	v_lshl_add_u32 v36, v36, 2, s50
	v_lshl_add_u32 v37, v37, 2, s51
	ds_read_b32 v124, v36
	ds_read_b32 v140, v37
	v_add_u32_e32 v34, 0xffffffa7, v33
	v_min_u32_e32 v38, 0x7f, v34
	v_min_u32_e32 v39, 0x9f, v34
	v_lshl_add_u32 v38, v38, 2, s50
	v_lshl_add_u32 v39, v39, 2, s51
	ds_read_b32 v125, v38
	ds_read_b32 v141, v39
	v_add_u32_e32 v34, 0xffffffa6, v33
	v_min_u32_e32 v40, 0x7f, v34
	v_min_u32_e32 v41, 0x9f, v34
	v_lshl_add_u32 v40, v40, 2, s50
	v_lshl_add_u32 v41, v41, 2, s51
	ds_read_b32 v126, v40
	ds_read_b32 v142, v41
	v_add_u32_e32 v34, 0xffffffa5, v33
	v_min_u32_e32 v42, 0x7f, v34
	v_min_u32_e32 v43, 0x9f, v34
	v_lshl_add_u32 v42, v42, 2, s50
	v_lshl_add_u32 v43, v43, 2, s51
	ds_read_b32 v127, v42
	ds_read_b32 v143, v43
	v_add_u32_e32 v34, 0xffffffb6, v33
	v_cmp_lt_i32_e64 s[6:7], -1, v34
	v_cmp_lt_i32_e64 s[60:61], 31, v34
	v_add_f32_e32 v118, v102, v118
	v_add_f32_e32 v134, v86, v134
	v_cndmask_b32_e64 v102, v47, v118, s[6:7]
	v_cndmask_b32_e64 v86, v47, v134, s[60:61]
	v_add_u32_e32 v34, 0xffffffb5, v33
	v_cmp_lt_i32_e64 s[6:7], -1, v34
	v_cmp_lt_i32_e64 s[60:61], 31, v34
	v_add_f32_e32 v119, v103, v119
	v_add_f32_e32 v135, v87, v135
	v_cndmask_b32_e64 v103, v47, v119, s[6:7]
	v_cndmask_b32_e64 v87, v47, v135, s[60:61]
	v_add_u32_e32 v34, 0xffffffb0, v33
	v_cmp_lt_i32_e64 s[6:7], -1, v34
	v_cmp_lt_i32_e64 s[60:61], 31, v34
	v_add_f32_e32 v120, v104, v120
	v_add_f32_e32 v136, v88, v136
	v_cndmask_b32_e64 v104, v47, v120, s[6:7]
	v_cndmask_b32_e64 v88, v47, v136, s[60:61]
	v_add_u32_e32 v34, 0xffffffaf, v33
	v_cmp_lt_i32_e64 s[6:7], -1, v34
	v_cmp_lt_i32_e64 s[60:61], 31, v34
	v_add_f32_e32 v121, v105, v121
	v_add_f32_e32 v137, v89, v137
	v_cndmask_b32_e64 v105, v47, v121, s[6:7]
	v_cndmask_b32_e64 v89, v47, v137, s[60:61]
	v_add_u32_e32 v34, 0xffffffae, v33
	v_cmp_lt_i32_e64 s[6:7], -1, v34
	v_cmp_lt_i32_e64 s[60:61], 31, v34
	v_add_f32_e32 v122, v106, v122
	v_add_f32_e32 v138, v90, v138
	v_cndmask_b32_e64 v106, v47, v122, s[6:7]
	v_cndmask_b32_e64 v90, v47, v138, s[60:61]
	v_add_u32_e32 v34, 0xffffffad, v33
	v_cmp_lt_i32_e64 s[6:7], -1, v34
	v_cmp_lt_i32_e64 s[60:61], 31, v34
	v_add_f32_e32 v123, v107, v123
	v_add_f32_e32 v139, v91, v139
	v_cndmask_b32_e64 v107, v47, v123, s[6:7]
	v_cndmask_b32_e64 v91, v47, v139, s[60:61]
	s_waitcnt lgkmcnt(0)
	v_add_u32_e32 v34, 0xffffffa8, v33
	v_cmp_lt_i32_e64 s[6:7], -1, v34
	v_cmp_lt_i32_e64 s[60:61], 31, v34
	v_add_f32_e32 v124, v108, v124
	v_add_f32_e32 v140, v92, v140
	v_cndmask_b32_e64 v108, v47, v124, s[6:7]
	v_cndmask_b32_e64 v92, v47, v140, s[60:61]
	v_add_u32_e32 v34, 0xffffffa7, v33
	v_cmp_lt_i32_e64 s[6:7], -1, v34
	v_cmp_lt_i32_e64 s[60:61], 31, v34
	v_add_f32_e32 v125, v109, v125
	v_add_f32_e32 v141, v93, v141
	v_cndmask_b32_e64 v109, v47, v125, s[6:7]
	v_cndmask_b32_e64 v93, v47, v141, s[60:61]
	v_add_u32_e32 v34, 0xffffffa6, v33
	v_cmp_lt_i32_e64 s[6:7], -1, v34
	v_cmp_lt_i32_e64 s[60:61], 31, v34
	v_add_f32_e32 v126, v110, v126
	v_add_f32_e32 v142, v94, v142
	v_cndmask_b32_e64 v110, v47, v126, s[6:7]
	v_cndmask_b32_e64 v94, v47, v142, s[60:61]
	v_add_u32_e32 v34, 0xffffffa5, v33
	v_cmp_lt_i32_e64 s[6:7], -1, v34
	v_cmp_lt_i32_e64 s[60:61], 31, v34
	v_add_f32_e32 v127, v111, v127
	v_add_f32_e32 v143, v95, v143
	v_cndmask_b32_e64 v111, v47, v127, s[6:7]
	v_cndmask_b32_e64 v95, v47, v143, s[60:61]

; #define AT_LOADK(t) do { kr0 = *(const v4u*)(kg + (size_t)(t) * 64 * 1024); kr1 = *(const v4u*)(kg + (size_t)(t) * 64 * 1024 + 32 * 1024); } while (0)
; #define AT_LOADV(t) do { vr0 = *(const v4u*)(vg + (t) * 64); vr1 = *(const v4u*)(vg + (size_t)64 * SEQ + (t) * 64); } while (0)
;     ...
;             if (!(AMODE & 4)) { if (t + 2 < NT) AT_LOADK(t + 2); if (t + 1 < NT) AT_LOADV(t + 1); }
.LBB0_468:
	v_sub_f32_e32 v34, v96, v214
	v_sub_f32_e32 v35, v97, v214
	v_sub_f32_e32 v36, v80, v214
	v_sub_f32_e32 v37, v81, v214
	v_exp_f32_e32 v34, v34
	v_exp_f32_e32 v35, v35
	v_exp_f32_e32 v42, v36
	v_exp_f32_e32 v43, v37
	v_lshl_add_u64 v[252:253], s[94:95], 1, v[178:179]
	global_load_dwordx4 v[168:171], v[252:253], off
	v_sub_f32_e32 v38, v98, v214
	v_sub_f32_e32 v39, v99, v214
	v_sub_f32_e32 v40, v82, v214
	v_sub_f32_e32 v41, v83, v214
	v_exp_f32_e32 v38, v38
	v_exp_f32_e32 v39, v39
	v_exp_f32_e32 v44, v40
	v_exp_f32_e32 v45, v41
	v_sub_f32_e32 v40, v100, v214
	v_sub_f32_e32 v41, v101, v214
	v_add_f32_e32 v36, 0, v34
	v_add_f32_e32 v37, 0, v35
	v_sub_f32_e32 v46, v84, v214
	v_sub_f32_e32 v47, v85, v214
	v_exp_f32_e32 v40, v40
	v_exp_f32_e32 v41, v41
	v_add_f32_e32 v36, v42, v36
	v_add_f32_e32 v37, v43, v37
	v_exp_f32_e32 v46, v46
	v_exp_f32_e32 v47, v47
	v_sub_f32_e32 v80, v102, v214
	v_sub_f32_e32 v81, v103, v214
	v_add_f32_e32 v36, v38, v36
	v_add_f32_e32 v37, v39, v37
	v_sub_f32_e32 v82, v86, v214
	v_sub_f32_e32 v83, v87, v214
	v_exp_f32_e32 v80, v80
	v_exp_f32_e32 v81, v81
	v_add_f32_e32 v36, v44, v36
	v_add_f32_e32 v37, v45, v37
	v_exp_f32_e32 v82, v82
	v_exp_f32_e32 v83, v83
	v_lshl_add_u64 v[252:253], s[94:95], 1, v[184:185]
	global_load_dwordx4 v[172:175], v[252:253], off
	v_sub_f32_e32 v84, v104, v214
	v_sub_f32_e32 v85, v105, v214
	v_add_f32_e32 v36, v40, v36
	v_add_f32_e32 v37, v41, v37
	v_sub_f32_e32 v86, v88, v214
	v_sub_f32_e32 v87, v89, v214
	v_exp_f32_e32 v84, v84
	v_exp_f32_e32 v85, v85
	v_add_f32_e32 v36, v46, v36
	v_add_f32_e32 v37, v47, v37
	v_exp_f32_e32 v86, v86
	v_exp_f32_e32 v87, v87
	v_sub_f32_e32 v88, v106, v214
	v_sub_f32_e32 v89, v107, v214
	v_add_f32_e32 v36, v80, v36
	v_add_f32_e32 v37, v81, v37
	v_sub_f32_e32 v90, v90, v214
	v_sub_f32_e32 v91, v91, v214
	v_exp_f32_e32 v88, v88
	v_exp_f32_e32 v89, v89
	v_add_f32_e32 v36, v82, v36
	v_add_f32_e32 v37, v83, v37
	v_exp_f32_e32 v90, v90
	v_exp_f32_e32 v91, v91
	v_sub_f32_e32 v96, v108, v214
	v_sub_f32_e32 v97, v109, v214
	v_add_f32_e32 v36, v84, v36
	v_add_f32_e32 v37, v85, v37
	v_sub_f32_e32 v92, v92, v214
	v_sub_f32_e32 v93, v93, v214
	v_exp_f32_e32 v96, v96
	v_exp_f32_e32 v97, v97
	v_add_f32_e32 v36, v86, v36
	v_add_f32_e32 v37, v87, v37
	v_exp_f32_e32 v92, v92
	v_exp_f32_e32 v93, v93
	v_add_f32_e32 v36, v88, v36
	v_add_f32_e32 v37, v89, v37
	v_sub_f32_e32 v94, v94, v214
	v_sub_f32_e32 v95, v95, v214
	v_add_f32_e32 v36, v90, v36
	v_add_f32_e32 v37, v91, v37
	v_exp_f32_e32 v94, v94
	v_add_f32_e32 v36, v96, v36
	v_add_f32_e32 v37, v97, v37
	v_exp_f32_e32 v95, v95
	v_add_f32_e32 v98, v92, v36
	v_add_f32_e32 v99, v93, v37
	v_sub_f32_e32 v36, v110, v214
	v_sub_f32_e32 v37, v111, v214
	v_add_u32_e32 v33, s49, v223
	v_exp_f32_e32 v100, v36
	v_exp_f32_e32 v101, v37
	v_add_u32_e32 v108, 0x8800, v33
	v_add_u32_e32 v109, 0x9800, v33
	v_cvt_pk_bf16_f32 v34, v34, v35
	v_cvt_pk_bf16_f32 v35, v38, v39
	v_cvt_pk_bf16_f32 v36, v40, v41
	v_cvt_pk_bf16_f32 v37, v80, v81
	v_cvt_pk_bf16_f32 v38, v84, v85
	v_cvt_pk_bf16_f32 v39, v88, v89
	v_cvt_pk_bf16_f32 v40, v96, v97
	v_cvt_pk_bf16_f32 v41, v100, v101
	v_cvt_pk_bf16_f32 v42, v42, v43
	v_cvt_pk_bf16_f32 v43, v44, v45
	v_cvt_pk_bf16_f32 v44, v46, v47
	v_cvt_pk_bf16_f32 v45, v82, v83
	v_cvt_pk_bf16_f32 v80, v86, v87
	v_cvt_pk_bf16_f32 v81, v90, v91
	v_cvt_pk_bf16_f32 v82, v92, v93
	v_cvt_pk_bf16_f32 v83, v94, v95
	s_setprio 0
	s_barrier
	ds_read_b128 v[84:87], v108
	ds_read_b128 v[88:91], v109 offset:512
	v_add_f32_e32 v46, v100, v98
	v_add_f32_e32 v47, v101, v99
	s_nop 0
	v_add_f32_e32 v46, v94, v46
	v_add_f32_e32 v47, v95, v47
	s_nop 0
	v_add_f32_e32 v46, v46, v47
	v_add_f32_e32 v250, v250, v46
	v_add_u32_e32 v46, 0xa800, v33
	v_add_u32_e32 v33, 0xb800, v33
	ds_read_b128 v[92:95], v46 offset:1024
	ds_read_b128 v[96:99], v33 offset:1536
	ds_read_b128 v[100:103], v108 offset:32
	ds_read_b128 v[104:107], v109 offset:544
	s_waitcnt lgkmcnt(5)
	v_mfma_f32_32x32x16_bf16 v[64:79], v[84:87], v[34:37], v[64:79]
	s_waitcnt lgkmcnt(4)
	v_mfma_f32_32x32x16_bf16 v[48:63], v[88:91], v[34:37], v[48:63]
	ds_read_b128 v[84:87], v46 offset:1056
	ds_read_b128 v[88:91], v33 offset:1568
	s_waitcnt lgkmcnt(5)
	v_mfma_f32_32x32x16_bf16 v[16:31], v[92:95], v[34:37], v[16:31]
	s_waitcnt lgkmcnt(4)
	v_mfma_f32_32x32x16_bf16 v[0:15], v[96:99], v[34:37], v[0:15]
	ds_read_b128 v[34:37], v108 offset:64
	ds_read_b128 v[92:95], v109 offset:576
	s_waitcnt lgkmcnt(5)
	v_mfma_f32_32x32x16_bf16 v[64:79], v[100:103], v[38:41], v[64:79]
	s_waitcnt lgkmcnt(4)
	v_mfma_f32_32x32x16_bf16 v[48:63], v[104:107], v[38:41], v[48:63]
	ds_read_b128 v[96:99], v46 offset:1088
	ds_read_b128 v[100:103], v33 offset:1600
	s_waitcnt lgkmcnt(5)
	v_mfma_f32_32x32x16_bf16 v[16:31], v[84:87], v[38:41], v[16:31]
	s_waitcnt lgkmcnt(4)
	v_mfma_f32_32x32x16_bf16 v[0:15], v[88:91], v[38:41], v[0:15]
	ds_read_b128 v[38:41], v108 offset:96
	ds_read_b128 v[84:87], v109 offset:608
	s_waitcnt lgkmcnt(5)
	v_mfma_f32_32x32x16_bf16 v[64:79], v[34:37], v[42:45], v[64:79]
	s_waitcnt lgkmcnt(4)
	v_mfma_f32_32x32x16_bf16 v[48:63], v[92:95], v[42:45], v[48:63]
	ds_read_b128 v[34:37], v46 offset:1120
	ds_read_b128 v[88:91], v33 offset:1632
	s_waitcnt lgkmcnt(5)
	v_mfma_f32_32x32x16_bf16 v[16:31], v[96:99], v[42:45], v[16:31]
	s_waitcnt lgkmcnt(4)
	v_mfma_f32_32x32x16_bf16 v[0:15], v[100:103], v[42:45], v[0:15]
	s_waitcnt lgkmcnt(3)
	v_mfma_f32_32x32x16_bf16 v[64:79], v[38:41], v[80:83], v[64:79]
	s_waitcnt lgkmcnt(2)
	v_mfma_f32_32x32x16_bf16 v[48:63], v[84:87], v[80:83], v[48:63]
	s_waitcnt lgkmcnt(1)
	v_mfma_f32_32x32x16_bf16 v[16:31], v[34:37], v[80:83], v[16:31]
	s_waitcnt lgkmcnt(0)
	v_mfma_f32_32x32x16_bf16 v[0:15], v[88:91], v[80:83], v[0:15]
